# MLA unit head: LDS-DMA lane offsets hoisted to phase init (28 VALU fewer between the unit barrier and the first QK MFMA)
# baseline (speedup 1.0000x reference)
; #define PH(n) if constexpr ((PHASE_MASK >> (n)) & 1)
; __global__ void __launch_bounds__(512, 2) fwd_mega(Args a) {
;     ...
;         PH(11) for (int L = vcu; L < 8 * 8 * 16; L += G) {
;             const int qb = L & 15, bh = L >> 4, b = bh >> 3, h = bh & 7; const size_t row0 = (size_t)b * SEQ + qb * 256;
;             attn_unit<96, 64, 1, true>(lds, Qb + row0 * 768 + h * 96, 768, Kbuf + (size_t)b * SEQ * 768 + h * 96, 768,
;                               Vt + (size_t)(b * 512 + h * 64) * 4096, 4096, SEQ, P + row0 * PW + PC_ZMLA + h * 64, P + row0 * PW + PC_ZMLA + h * 64, PW, wave);
.LBB0_859:
	s_cmpk_gt_i32 s87, 0x3ff
	s_cbranch_scc1 .LBB0_895
	s_add_u32 s3, s6, 0x5000000
	s_addc_u32 s24, s7, 0
	s_add_u32 s25, s6, 0x2000000
	s_addc_u32 s48, s7, 0
	s_add_u32 s49, s10, 0x17000000
	s_addc_u32 s50, s11, 0
	v_add_u32_e32 v0, 64, v187
	s_add_u32 s28, s6, 0x2030000
	v_cmp_lt_i32_e32 vcc, v185, v0
	s_addc_u32 s29, s7, 0
	s_add_u32 s30, s10, 0x17000100
	v_cndmask_b32_e32 v0, v184, v185, vcc
	v_lshlrev_b32_e32 v162, 2, v0
	s_addc_u32 s31, s11, 0
	s_movk_i32 s51, 0x600
	v_mov_b32_e32 v149, 0
	s_mov_b32 s64, 0
	s_mov_b32 s65, 0
	v_mov_b32_e32 v241, 0x10000
	ds_write_b32 v241, v149
	s_mov_b32 s98, 0x13b13b14
	s_mov_b32 s99, 0x15555556
	v_add_u32_e32 v235, s79, v184
	v_mul_hi_u32 v236, v235, s98
	v_mul_u32_u24_e32 v237, 13, v236
	v_sub_u32_e32 v237, v235, v237
	v_min_u32_e32 v237, 11, v237
	v_mul_u32_u24_e32 v236, 0x600, v236
	v_lshl_add_u32 v238, v237, 4, v236
	v_mul_hi_u32 v236, v235, s99
	v_mul_u32_u24_e32 v237, 12, v236
	v_sub_u32_e32 v237, v235, v237
	v_mul_u32_u24_e32 v236, 0x600, v236
	v_lshl_add_u32 v236, v237, 4, v236
	v_sub_u32_e32 v238, v238, v236
	v_add_u32_e32 v235, 0x200, v235
	v_mul_hi_u32 v236, v235, s98
	v_mul_u32_u24_e32 v237, 13, v236
	v_sub_u32_e32 v237, v235, v237
	v_min_u32_e32 v237, 11, v237
	v_mul_u32_u24_e32 v236, 0x600, v236
	v_lshl_add_u32 v239, v237, 4, v236
	v_mul_hi_u32 v236, v235, s99
	v_mul_u32_u24_e32 v237, 12, v236
	v_sub_u32_e32 v237, v235, v237
	v_mul_u32_u24_e32 v236, 0x600, v236
	v_lshl_add_u32 v236, v237, 4, v236
	v_sub_u32_e32 v239, v239, v236
	s_movk_i32 s52, 0x300
	s_mov_b32 s53, 0x2aaaaaab
	s_movk_i32 s54, 0xff
	s_movk_i32 s55, 0x100
	s_movk_i32 s56, 0xd0
	s_movk_i32 s57, 0x90
	s_mov_b32 s58, 0xaaaaaaab
	s_mov_b32 s59, 0x41000000
	s_mov_b64 s[34:35], 0x18000
	s_mov_b64 s[36:37], 0x80
	s_movk_i32 s60, 0x2800
	v_mov_b32_e32 v163, 0xc0
	s_mov_b32 s61, s87
	s_branch .LBB0_863

; template <int DQK, int DV, int RH, bool NEGM> ...
;     ...
;     const int NT = nkv / 64;
;     AT_GLOAD(0); AT_LSTORE(0, 0); __syncthreads();
.LBB0_881:
	s_or_b64 exec, exec, s[42:43]
	v_pk_add_f32 v[48:49], v[48:49], v[54:55]
	v_pk_add_f32 v[64:65], v[128:129], v[64:65]
	v_pk_add_f32 v[48:49], v[58:59], v[48:49] op_sel_hi:[0,1]
	v_pk_add_f32 v[52:53], v[52:53], v[56:57]
	v_pk_add_f32 v[48:49], v[64:65], v[48:49]
	v_pk_add_f32 v[70:71], v[118:119], v[70:71]
	v_pk_add_f32 v[48:49], v[52:53], v[48:49]
	v_add_u32_e32 v54, v136, v135
	v_pk_add_f32 v[150:151], v[70:71], v[48:49]
	v_add_u32_e32 v48, 0x8c00, v166
	s_waitcnt vmcnt(0)
	ds_write2_b64 v48, v[74:75], v[76:77] offset1:2
	v_mul_lo_u32 v48, v54, 12
	v_sub_u32_e32 v52, v133, v48
	s_lshr_b32 s21, s61, 4
	v_lshlrev_b32_e32 v48, 3, v52
	v_lshlrev_b32_e32 v175, 4, v52
	v_mov_b64_e32 v[52:53], s[40:41]
	s_and_b32 s42, s21, 7
	v_mul_lo_u32 v174, v54, s56
	v_mad_i64_i32 v[54:55], s[40:41], v54, s51, v[52:53]
	v_pk_add_f32 v[50:51], v[50:51], v[62:63]
	v_ashrrev_i32_e32 v49, 31, v48
	v_mad_u64_u32 v[54:55], s[40:41], s42, v163, v[54:55]
	v_pk_add_f32 v[66:67], v[130:131], v[66:67]
	v_pk_add_f32 v[50:51], v[58:59], v[50:51] op_sel_hi:[0,1]
	v_lshl_add_u64 v[48:49], v[48:49], 1, v[54:55]
	v_pk_add_f32 v[56:57], v[116:117], v[68:69]
	v_pk_add_f32 v[50:51], v[66:67], v[50:51]
	v_mov_b32_e32 v154, v48
	v_mad_i64_i32 v[48:49], s[40:41], v59, s51, v[52:53]
	v_pk_add_f32 v[60:61], v[60:61], v[72:73]
	v_pk_add_f32 v[50:51], v[56:57], v[50:51]
	s_lshl_b32 s43, s42, 6
	v_mad_u64_u32 v[48:49], s[40:41], s42, v163, v[48:49]
	v_pk_add_f32 v[152:153], v[60:61], v[50:51]
	v_lshlrev_b32_e32 v50, 3, v112
	s_add_i32 s40, s47, s43
	v_ashrrev_i32_e32 v51, 31, v50
	s_ashr_i32 s41, s40, 31
	v_lshl_add_u64 v[48:49], v[50:51], 1, v[48:49]
	s_lshl_b64 s[40:41], s[40:41], 13
	v_and_b32_e32 v50, 7, v132
	v_mov_b32_e32 v156, v48
	v_lshl_add_u64 v[48:49], v[78:79], 0, s[40:41]
	v_lshlrev_b32_e32 v148, 4, v50
	v_lshl_add_u64 v[48:49], v[48:49], 0, v[148:149]
	v_mul_u32_u24_e32 v173, 0x90, v134
	s_mov_b32 s21, 1
	v_mov_b32_e32 v158, v48
	s_mov_b32 s42, 2
	s_mov_b32 s43, 1
	s_waitcnt lgkmcnt(0)
	s_barrier
	s_mov_b64 s[98:99], s[28:29]
	s_mov_b64 s[100:101], s[30:31]
	v_add_u32_e32 v244, v174, v175
	v_add_u32_e32 v245, v171, v172
	v_add_u32_e32 v241, v238, v154
	v_add_u32_e32 v242, v239, v156
	s_lshl_b32 s70, s79, 4
	s_add_i32 s73, s70, 0x2000
	s_cmpk_lt_u32 s79, 0x140
	s_cselect_b32 s73, s73, 0x12000
	s_cselect_b32 s74, 0x3400, 0
	s_cmp_eq_u32 s65, 0
	s_cbranch_scc0 .Lmlac_loop
